# single-counter barrier tail (poll bound raised to the original 2^18) + hand-written gdn final stage
# speedup vs baseline: 1.0138x; 1.0015x over previous
; __device__ __forceinline__ unsigned xb_ld(unsigned* p)              { return __hip_atomic_load(p, __ATOMIC_RELAXED, __HIP_MEMORY_SCOPE_AGENT); }
; __device__ __forceinline__ unsigned xb_add(unsigned* p, unsigned v) { return __hip_atomic_fetch_add(p, v, __ATOMIC_RELAXED, __HIP_MEMORY_SCOPE_AGENT); }
; #define XB_SPIN(cond, bar) do { unsigned _sp = 0; while (cond) { __builtin_amdgcn_s_sleep(1); \
;     if ((++_sp & 255u) == 0u) { if (xb_ld(&(bar)[XB_TMO])) break; if (_sp > XB_SPIN_CAP) { atomicAdd(&(bar)[XB_TMO], 1u); break; } } } } while (0)
; __device__ __forceinline__ void xcd_barrier(const XcdBarrier& b) {
;     ...
;         const unsigned old = xb_add(&bar[XB_XSUB(b.x)], 1u);
;         const unsigned gen = old / nloc;
;         if (old + 1u == (gen + 1u) * nloc) {
;             __builtin_amdgcn_fence(__ATOMIC_RELEASE, "agent");
;             asm volatile("s_waitcnt vmcnt(0)" ::: "memory");
;             const unsigned og = xb_add(&bar[XB_TOP], 1u);
;             const unsigned tg = og / nx;
;             if (og + 1u == (tg + 1u) * nx) xb_add(&bar[XB_TOPGEN], 1u);
;             else XB_SPIN(xb_ld(&bar[XB_TOPGEN]) == tg, bar);
;             __builtin_amdgcn_fence(__ATOMIC_ACQUIRE, "agent");
;             xb_add(&bar[XB_XGEN(b.x)], 1u);
;             asm volatile("s_waitcnt vmcnt(0)" ::: "memory");
;         } else {
;             XB_SPIN(xb_ld(&bar[XB_XGEN(b.x)]) == gen, bar);
;             __builtin_amdgcn_fence(__ATOMIC_ACQUIRE, "agent");
;             asm volatile("s_waitcnt vmcnt(0)" ::: "memory");
.Lgs0_loop:
	global_load_dword v6, v157, s[8:9] sc1
	s_waitcnt vmcnt(0)
	v_cmp_ge_u32_e32 vcc, v6, v12
	s_cbranch_vccnz .Lgs0_done
	s_sleep 1
	s_add_i32 s6, s6, 1
	s_cmp_lt_u32 s6, 0x40000
	s_cbranch_scc1 .Lgs0_loop
